# sample-MLA: next-tile global loads interleaved into the LDS store phase (on top of pipelined LDS reads)
# baseline (speedup 1.0000x reference)
.LBB0_939:
	s_add_i32 s12, s11, 0xffffff80
	v_add_u32_e32 v205, v226, v204
	v_lshl_add_u64 v[130:131], s[34:35], 0, v[214:215]
	v_add_co_u32_e32 v130, vcc, 0x16d10000, v130
	s_nop 1
	v_addc_co_u32_e32 v131, vcc, 0, v131, vcc
	v_lshl_add_u64 v[132:133], v[130:131], 0, s[24:25]
	v_lshl_add_u64 v[134:135], v[132:133], 0, s[24:25]
	v_lshl_add_u64 v[136:137], v[134:135], 0, s[24:25]
	v_lshl_add_u64 v[138:139], v[136:137], 0, s[24:25]
	v_lshl_add_u64 v[140:141], v[138:139], 0, s[24:25]
	v_lshl_add_u64 v[142:143], v[140:141], 0, s[24:25]
	v_lshl_add_u64 v[144:145], v[142:143], 0, s[24:25]
	v_lshl_add_u64 v[146:147], s[34:35], 0, v[212:213]
	v_cmp_lt_i32_e32 vcc, s12, v227
	s_waitcnt lgkmcnt(0)
	s_barrier
	s_waitcnt vmcnt(7)
	ds_write_b128 v205, v[166:169]
	s_waitcnt vmcnt(6)
	ds_write_b128 v205, v[170:173] offset:9472
	global_load_dwordx4 v[166:169], v[130:131], off
	s_waitcnt vmcnt(6)
	ds_write_b128 v205, v[174:177] offset:18944
	global_load_dwordx4 v[170:173], v[132:133], off
	s_waitcnt vmcnt(6)
	ds_write_b128 v205, v[178:181] offset:28416
	global_load_dwordx4 v[174:177], v[134:135], off
	s_waitcnt vmcnt(6)
	ds_write_b128 v205, v[182:185] offset:37888
	global_load_dwordx4 v[178:181], v[136:137], off
	s_waitcnt vmcnt(6)
	ds_write_b128 v205, v[186:189] offset:47360
	global_load_dwordx4 v[182:185], v[138:139], off
	s_waitcnt vmcnt(6)
	ds_write_b128 v205, v[190:193] offset:56832
	global_load_dwordx4 v[186:189], v[140:141], off
	s_waitcnt vmcnt(6)
	ds_write_b128 v228, v[194:197]
	global_load_dwordx4 v[190:193], v[142:143], off
	s_and_saveexec_b64 s[6:7], vcc
	s_waitcnt vmcnt(7)
	v_add_u32_e32 v148, v225, v210
	ds_write_b128 v148, v[162:165] offset:512
	s_or_b64 exec, exec, s[6:7]
	global_load_dwordx4 v[194:197], v[144:145], off
	v_cmp_lt_i32_e32 vcc, s11, v227
	s_and_saveexec_b64 s[6:7], vcc
	s_cbranch_execz .LBB0_943
	global_load_dwordx4 v[162:165], v[146:147], off
.LBB0_943:
	s_or_b64 exec, exec, s[6:7]
	s_waitcnt lgkmcnt(0)
	s_barrier
	s_cmp_ge_i32 s12, s10
	s_cbranch_scc1 .LBB0_947
	v_add_u32_e32 v229, v224, v198
	ds_read_b128 v[130:133], v229
	ds_read_b128 v[134:137], v223
	ds_read_b128 v[146:149], v229 offset:32
	ds_read_b128 v[150:153], v223 offset:1024
	ds_read_b128 v[232:235], v229 offset:64
	ds_read_b128 v[236:239], v223 offset:2048
	ds_read_b128 v[240:243], v229 offset:96
	ds_read_b128 v[246:249], v223 offset:3072
	s_waitcnt lgkmcnt(6)
	v_mfma_f32_32x32x16_bf16 v[130:145], v[130:133], v[134:137], 0
	s_waitcnt lgkmcnt(4)
	v_mfma_f32_32x32x16_bf16 v[146:161], v[146:149], v[150:153], 0
	s_waitcnt lgkmcnt(2)
	v_mfma_f32_32x32x16_bf16 v[130:145], v[232:235], v[236:239], v[130:145]
	ds_read_b128 v[232:235], v229 offset:128
	ds_read_b128 v[236:239], v223 offset:4096
	s_waitcnt lgkmcnt(2)
	v_mfma_f32_32x32x16_bf16 v[146:161], v[240:243], v[246:249], v[146:161]
	ds_read_b128 v[240:243], v229 offset:160
	ds_read_b128 v[246:249], v223 offset:5120
	s_waitcnt lgkmcnt(2)
	v_mfma_f32_32x32x16_bf16 v[130:145], v[232:235], v[236:239], v[130:145]
	ds_read_b128 v[232:235], v229 offset:192
	ds_read_b128 v[236:239], v223 offset:6144
	s_waitcnt lgkmcnt(2)
	v_mfma_f32_32x32x16_bf16 v[146:161], v[240:243], v[246:249], v[146:161]
	ds_read_b128 v[240:243], v229 offset:224
	ds_read_b128 v[246:249], v223 offset:7168
	s_waitcnt lgkmcnt(2)
	v_mfma_f32_32x32x16_bf16 v[130:145], v[232:235], v[236:239], v[130:145]
	ds_read_b128 v[232:235], v229 offset:256
	ds_read_b128 v[236:239], v223 offset:8192
	s_waitcnt lgkmcnt(2)
	v_mfma_f32_32x32x16_bf16 v[146:161], v[240:243], v[246:249], v[146:161]
	ds_read_b128 v[240:243], v229 offset:288
	ds_read_b128 v[246:249], v223 offset:9216
	s_waitcnt lgkmcnt(2)
	v_mfma_f32_32x32x16_bf16 v[130:145], v[232:235], v[236:239], v[130:145]
	ds_read_b128 v[232:235], v229 offset:320
	ds_read_b128 v[236:239], v223 offset:10240
	s_waitcnt lgkmcnt(2)
	v_mfma_f32_32x32x16_bf16 v[146:161], v[240:243], v[246:249], v[146:161]
	ds_read_b128 v[240:243], v229 offset:352
	ds_read_b128 v[246:249], v223 offset:11264
	s_waitcnt lgkmcnt(2)
	v_mfma_f32_32x32x16_bf16 v[130:145], v[232:235], v[236:239], v[130:145]
	ds_read_b128 v[232:235], v229 offset:384
	ds_read_b128 v[236:239], v223 offset:12288
	s_waitcnt lgkmcnt(2)
	v_mfma_f32_32x32x16_bf16 v[146:161], v[240:243], v[246:249], v[146:161]
	ds_read_b128 v[240:243], v229 offset:416
	ds_read_b128 v[246:249], v223 offset:13312
	s_waitcnt lgkmcnt(2)
	v_mfma_f32_32x32x16_bf16 v[130:145], v[232:235], v[236:239], v[130:145]
	ds_read_b128 v[232:235], v229 offset:448
	ds_read_b128 v[236:239], v223 offset:14336
	s_waitcnt lgkmcnt(2)
	v_mfma_f32_32x32x16_bf16 v[146:161], v[240:243], v[246:249], v[146:161]
	ds_read_b128 v[240:243], v229 offset:480
	ds_read_b128 v[246:249], v223 offset:15360
	s_waitcnt lgkmcnt(2)
	v_mfma_f32_32x32x16_bf16 v[130:145], v[232:235], v[236:239], v[130:145]
	ds_read_b128 v[232:235], v229 offset:512
	ds_read_b128 v[236:239], v223 offset:16384
	s_waitcnt lgkmcnt(2)
	v_mfma_f32_32x32x16_bf16 v[146:161], v[240:243], v[246:249], v[146:161]
	ds_read_b128 v[240:243], v229 offset:544
	ds_read_b128 v[246:249], v223 offset:17408
	s_waitcnt lgkmcnt(2)
	v_mfma_f32_32x32x16_bf16 v[130:145], v[232:235], v[236:239], v[130:145]
	s_waitcnt lgkmcnt(0)
	v_mfma_f32_32x32x16_bf16 v[146:161], v[240:243], v[246:249], v[146:161]
	s_nop 11
	v_pk_add_f32 v[146:147], v[130:131], v[146:147]
	v_pk_add_f32 v[132:133], v[132:133], v[148:149]
	v_max_f32_e32 v130, v146, v147
	v_pk_add_f32 v[134:135], v[134:135], v[150:151]
	v_max3_f32 v130, v130, v132, v133
	v_pk_add_f32 v[136:137], v[136:137], v[152:153]
	v_max3_f32 v130, v130, v134, v135
	v_mbcnt_hi_u32_b32 v131, -1, v217
	v_pk_add_f32 v[138:139], v[138:139], v[154:155]
	v_max3_f32 v130, v130, v136, v137
	v_and_b32_e32 v149, 64, v131
	v_pk_add_f32 v[140:141], v[140:141], v[156:157]
	v_max3_f32 v130, v130, v138, v139
	v_xor_b32_e32 v148, 32, v131
	v_add_u32_e32 v149, 64, v149
	v_pk_add_f32 v[142:143], v[142:143], v[158:159]
	v_max3_f32 v130, v130, v140, v141
	v_cmp_lt_i32_e32 vcc, v148, v149
	v_pk_add_f32 v[144:145], v[144:145], v[160:161]
	v_max3_f32 v130, v130, v142, v143
	v_cndmask_b32_e32 v131, v131, v148, vcc
	v_max3_f32 v130, v130, v144, v145
	v_lshlrev_b32_e32 v131, 2, v131
	ds_bpermute_b32 v131, v131, v130
	s_waitcnt lgkmcnt(0)
	ds_read_b64_tr_b16 v[232:233], v222
	ds_read_b64_tr_b16 v[234:235], v222 offset:4736
	ds_read_b64_tr_b16 v[236:237], v222 offset:64
	ds_read_b64_tr_b16 v[238:239], v222 offset:4800
	ds_read_b64_tr_b16 v[240:241], v222 offset:128
	ds_read_b64_tr_b16 v[242:243], v222 offset:4864
	ds_read_b64_tr_b16 v[246:247], v222 offset:192
	ds_read_b64_tr_b16 v[248:249], v222 offset:4928
	v_max3_f32 v229, v230, v130, v131
	v_sub_f32_e32 v130, v230, v229
	v_exp_f32_e32 v130, v130
	s_nop 0
	v_cmp_neq_f32_e32 vcc, 1.0, v130
	s_cbranch_vccz .LBB0_946
	v_pk_mul_f32 v[128:129], v[128:129], v[130:131] op_sel_hi:[1,0]
	v_pk_mul_f32 v[126:127], v[126:127], v[130:131] op_sel_hi:[1,0]
	v_pk_mul_f32 v[124:125], v[124:125], v[130:131] op_sel_hi:[1,0]
	v_pk_mul_f32 v[122:123], v[122:123], v[130:131] op_sel_hi:[1,0]
	v_pk_mul_f32 v[120:121], v[120:121], v[130:131] op_sel_hi:[1,0]
	v_pk_mul_f32 v[118:119], v[118:119], v[130:131] op_sel_hi:[1,0]
	v_pk_mul_f32 v[116:117], v[116:117], v[130:131] op_sel_hi:[1,0]
	v_pk_mul_f32 v[114:115], v[114:115], v[130:131] op_sel_hi:[1,0]
	v_pk_mul_f32 v[112:113], v[112:113], v[130:131] op_sel_hi:[1,0]
	v_pk_mul_f32 v[110:111], v[110:111], v[130:131] op_sel_hi:[1,0]
	v_pk_mul_f32 v[108:109], v[108:109], v[130:131] op_sel_hi:[1,0]
	v_pk_mul_f32 v[106:107], v[106:107], v[130:131] op_sel_hi:[1,0]
	v_pk_mul_f32 v[104:105], v[104:105], v[130:131] op_sel_hi:[1,0]
	v_pk_mul_f32 v[102:103], v[102:103], v[130:131] op_sel_hi:[1,0]
	v_pk_mul_f32 v[100:101], v[100:101], v[130:131] op_sel_hi:[1,0]
	v_pk_mul_f32 v[98:99], v[98:99], v[130:131] op_sel_hi:[1,0]
	v_pk_mul_f32 v[96:97], v[96:97], v[130:131] op_sel_hi:[1,0]
	v_pk_mul_f32 v[94:95], v[94:95], v[130:131] op_sel_hi:[1,0]
	v_pk_mul_f32 v[92:93], v[92:93], v[130:131] op_sel_hi:[1,0]
	v_pk_mul_f32 v[90:91], v[90:91], v[130:131] op_sel_hi:[1,0]
	v_pk_mul_f32 v[88:89], v[88:89], v[130:131] op_sel_hi:[1,0]
	v_pk_mul_f32 v[86:87], v[86:87], v[130:131] op_sel_hi:[1,0]
	v_pk_mul_f32 v[84:85], v[84:85], v[130:131] op_sel_hi:[1,0]
	v_pk_mul_f32 v[82:83], v[82:83], v[130:131] op_sel_hi:[1,0]
	v_pk_mul_f32 v[80:81], v[80:81], v[130:131] op_sel_hi:[1,0]
	v_pk_mul_f32 v[78:79], v[78:79], v[130:131] op_sel_hi:[1,0]
	v_pk_mul_f32 v[76:77], v[76:77], v[130:131] op_sel_hi:[1,0]
	v_pk_mul_f32 v[74:75], v[74:75], v[130:131] op_sel_hi:[1,0]
	v_pk_mul_f32 v[72:73], v[72:73], v[130:131] op_sel_hi:[1,0]
	v_pk_mul_f32 v[70:71], v[70:71], v[130:131] op_sel_hi:[1,0]
	v_pk_mul_f32 v[68:69], v[68:69], v[130:131] op_sel_hi:[1,0]
	v_pk_mul_f32 v[66:67], v[66:67], v[130:131] op_sel_hi:[1,0]
	v_pk_mul_f32 v[64:65], v[64:65], v[130:131] op_sel_hi:[1,0]
	v_pk_mul_f32 v[62:63], v[62:63], v[130:131] op_sel_hi:[1,0]
	v_pk_mul_f32 v[60:61], v[60:61], v[130:131] op_sel_hi:[1,0]
	v_pk_mul_f32 v[58:59], v[58:59], v[130:131] op_sel_hi:[1,0]
	v_pk_mul_f32 v[56:57], v[56:57], v[130:131] op_sel_hi:[1,0]
	v_pk_mul_f32 v[54:55], v[54:55], v[130:131] op_sel_hi:[1,0]
	v_pk_mul_f32 v[52:53], v[52:53], v[130:131] op_sel_hi:[1,0]
	v_pk_mul_f32 v[50:51], v[50:51], v[130:131] op_sel_hi:[1,0]
	v_pk_mul_f32 v[48:49], v[48:49], v[130:131] op_sel_hi:[1,0]
	v_pk_mul_f32 v[46:47], v[46:47], v[130:131] op_sel_hi:[1,0]
	v_pk_mul_f32 v[44:45], v[44:45], v[130:131] op_sel_hi:[1,0]
	v_pk_mul_f32 v[42:43], v[42:43], v[130:131] op_sel_hi:[1,0]
	v_pk_mul_f32 v[40:41], v[40:41], v[130:131] op_sel_hi:[1,0]
	v_pk_mul_f32 v[38:39], v[38:39], v[130:131] op_sel_hi:[1,0]
	v_pk_mul_f32 v[36:37], v[36:37], v[130:131] op_sel_hi:[1,0]
	v_pk_mul_f32 v[34:35], v[34:35], v[130:131] op_sel_hi:[1,0]
	v_pk_mul_f32 v[32:33], v[32:33], v[130:131] op_sel_hi:[1,0]
	v_pk_mul_f32 v[30:31], v[30:31], v[130:131] op_sel_hi:[1,0]
	v_pk_mul_f32 v[28:29], v[28:29], v[130:131] op_sel_hi:[1,0]
	v_pk_mul_f32 v[26:27], v[26:27], v[130:131] op_sel_hi:[1,0]
	v_pk_mul_f32 v[24:25], v[24:25], v[130:131] op_sel_hi:[1,0]
	v_pk_mul_f32 v[22:23], v[22:23], v[130:131] op_sel_hi:[1,0]
	v_pk_mul_f32 v[20:21], v[20:21], v[130:131] op_sel_hi:[1,0]
	v_pk_mul_f32 v[18:19], v[18:19], v[130:131] op_sel_hi:[1,0]
	v_pk_mul_f32 v[16:17], v[16:17], v[130:131] op_sel_hi:[1,0]
	v_pk_mul_f32 v[14:15], v[14:15], v[130:131] op_sel_hi:[1,0]
	v_pk_mul_f32 v[12:13], v[12:13], v[130:131] op_sel_hi:[1,0]
	v_pk_mul_f32 v[10:11], v[10:11], v[130:131] op_sel_hi:[1,0]
	v_pk_mul_f32 v[8:9], v[8:9], v[130:131] op_sel_hi:[1,0]
	v_pk_mul_f32 v[6:7], v[6:7], v[130:131] op_sel_hi:[1,0]
	v_pk_mul_f32 v[4:5], v[4:5], v[130:131] op_sel_hi:[1,0]
	v_pk_mul_f32 v[2:3], v[2:3], v[130:131] op_sel_hi:[1,0]
